# E43: grid-barrier XDONE polling keeps two poll batches in flight half a latency apart (finer detection granularity)
# speedup vs baseline: 1.0044x; 1.0041x over previous
.LBB0_168:
	s_or_b64 exec, exec, s[4:5]
	v_readlane_b32 s4, v255, 35
	v_readlane_b32 s5, v255, 36
	s_add_u32 s6, s4, 0x3400
	s_addc_u32 s7, s5, 0
	s_mov_b64 s[4:5], 0
	v_mov_b64_e32 v[0:1], s[6:7]
	s_movk_i32 s21, 0x80
	s_mov_b32 s22, 0x8000
	v_mov_b32_e32 v4, 0
	s_waitcnt vmcnt(0)
	s_mov_b32 s101, 0
	global_load_dwordx4 v[64:67], v[0:1], off sc1
	global_load_dwordx4 v[68:71], v[0:1], off offset:16 sc1
	global_load_dwordx4 v[72:75], v[0:1], off offset:32 sc1
	global_load_dwordx4 v[76:79], v[0:1], off offset:48 sc1
	s_sleep 16
	global_load_dwordx4 v[80:83], v[0:1], off sc1
	global_load_dwordx4 v[84:87], v[0:1], off offset:16 sc1
	global_load_dwordx4 v[88:91], v[0:1], off offset:32 sc1
	global_load_dwordx4 v[92:95], v[0:1], off offset:48 sc1
	s_branch .LBB0_171

.LBB0_171:
	s_xor_b32 s101, s101, 1
	s_cmp_eq_u32 s101, 0
	s_cbranch_scc1 .Lpp_odd_1
	s_waitcnt vmcnt(4)
	v_mov_b32_e32 v6, v64
	v_mov_b32_e32 v7, v65
	v_mov_b32_e32 v8, v66
	v_mov_b32_e32 v9, v67
	v_mov_b32_e32 v10, v68
	v_mov_b32_e32 v11, v69
	v_mov_b32_e32 v12, v70
	v_mov_b32_e32 v13, v71
	v_mov_b32_e32 v14, v72
	v_mov_b32_e32 v15, v73
	v_mov_b32_e32 v16, v74
	v_mov_b32_e32 v17, v75
	v_mov_b32_e32 v18, v76
	v_mov_b32_e32 v19, v77
	v_mov_b32_e32 v20, v78
	v_mov_b32_e32 v21, v79
	global_load_dwordx4 v[64:67], v[0:1], off sc1
	global_load_dwordx4 v[68:71], v[0:1], off offset:16 sc1
	global_load_dwordx4 v[72:75], v[0:1], off offset:32 sc1
	global_load_dwordx4 v[76:79], v[0:1], off offset:48 sc1
	s_branch .Lpp_join_1
.Lpp_odd_1:
	s_waitcnt vmcnt(4)
	v_mov_b32_e32 v6, v80
	v_mov_b32_e32 v7, v81
	v_mov_b32_e32 v8, v82
	v_mov_b32_e32 v9, v83
	v_mov_b32_e32 v10, v84
	v_mov_b32_e32 v11, v85
	v_mov_b32_e32 v12, v86
	v_mov_b32_e32 v13, v87
	v_mov_b32_e32 v14, v88
	v_mov_b32_e32 v15, v89
	v_mov_b32_e32 v16, v90
	v_mov_b32_e32 v17, v91
	v_mov_b32_e32 v18, v92
	v_mov_b32_e32 v19, v93
	v_mov_b32_e32 v20, v94
	v_mov_b32_e32 v21, v95
	global_load_dwordx4 v[80:83], v[0:1], off sc1
	global_load_dwordx4 v[84:87], v[0:1], off offset:16 sc1
	global_load_dwordx4 v[88:91], v[0:1], off offset:32 sc1
	global_load_dwordx4 v[92:95], v[0:1], off offset:48 sc1
.Lpp_join_1:
	s_or_b64 s[10:11], s[10:11], exec
	v_sub_u32_e32 v9, v9, v3
	v_sub_u32_e32 v5, v6, v3
	v_lshrrev_b32_e32 v9, 28, v9
	v_sub_u32_e32 v13, v13, v3
	v_sub_u32_e32 v17, v17, v3
	v_sub_u32_e32 v6, v10, v3
	v_sub_u32_e32 v10, v14, v3
	v_lshrrev_b32_e32 v5, 31, v5
	v_sub_u32_e32 v14, v18, v3
	v_sub_u32_e32 v18, v19, v3
	v_sub_u32_e32 v8, v8, v3
	v_sub_u32_e32 v12, v12, v3
	v_sub_u32_e32 v19, v20, v3
	v_and_b32_e32 v9, 8, v9
	v_and_b32_sdwa v13, v13, s21 dst_sel:DWORD dst_unused:UNUSED_PAD src0_sel:BYTE_3 src1_sel:DWORD
	v_lshrrev_b32_e32 v17, 20, v17
	v_sub_u32_e32 v20, v21, v3
	v_lshrrev_b32_e32 v8, 29, v8
	v_lshrrev_b32_e32 v12, 25, v12
	v_sub_u32_e32 v16, v16, v3
	v_and_b32_e32 v17, 0x800, v17
	v_and_b32_sdwa v20, v20, s22 dst_sel:DWORD dst_unused:UNUSED_PAD src0_sel:WORD_1 src1_sel:DWORD
	v_or3_b32 v5, v13, v5, v9
	v_sub_u32_e32 v7, v7, v3
	v_sub_u32_e32 v11, v11, v3
	v_and_b32_e32 v8, 4, v8
	v_and_b32_e32 v12, 64, v12
	v_lshrrev_b32_e32 v16, 21, v16
	v_lshrrev_b32_e32 v19, 17, v19
	v_or3_b32 v5, v5, v17, v20
	v_lshrrev_b32_e32 v7, 30, v7
	v_lshrrev_b32_e32 v11, 26, v11
	v_sub_u32_e32 v15, v15, v3
	v_and_b32_e32 v16, 0x400, v16
	v_and_b32_e32 v19, 0x4000, v19
	v_or3_b32 v5, v5, v12, v8
	v_and_b32_e32 v7, 2, v7
	v_and_b32_e32 v11, 32, v11
	v_lshrrev_b32_e32 v15, 22, v15
	v_lshrrev_b32_e32 v18, 18, v18
	v_or3_b32 v5, v5, v16, v19
	v_lshrrev_b32_e32 v6, 27, v6
	v_lshrrev_b32_e32 v10, 23, v10
	v_and_b32_e32 v15, 0x200, v15
	v_and_b32_e32 v18, 0x2000, v18
	v_or3_b32 v5, v5, v11, v7
	v_and_b32_e32 v6, 16, v6
	v_and_b32_e32 v10, 0x100, v10
	v_lshrrev_b32_e32 v14, 19, v14
	v_or3_b32 v5, v5, v15, v18
	v_and_b32_e32 v14, 0x1000, v14
	v_or3_b32 v5, v5, v6, v10
	s_waitcnt lgkmcnt(0)
	v_bitop3_b32 v5, v5, v2, v14 bitop3:0xc8
	s_nop 0
	v_readfirstlane_b32 s99, v5
	s_lshr_b32 s99, s99, s98
	s_and_b32 s99, s99, 1
	s_or_b32 s99, s99, s100
	s_cmp_lg_u32 s99, 0
	s_cbranch_scc1 .Lxinv_skip_1
	buffer_inv sc1
	s_waitcnt vmcnt(0)
	s_mov_b32 s100, 1

.LBB0_2344:
	s_or_b64 exec, exec, s[2:3]
	v_readlane_b32 s2, v255, 35
	v_readlane_b32 s3, v255, 36
	s_add_u32 s4, s2, 0x3400
	s_addc_u32 s5, s3, 0
	s_mov_b64 s[2:3], 0
	v_mov_b64_e32 v[0:1], s[4:5]
	s_movk_i32 s19, 0x80
	s_mov_b32 s20, 0x8000
	v_mov_b32_e32 v4, 0
	s_waitcnt vmcnt(0)
	s_mov_b32 s101, 0
	global_load_dwordx4 v[64:67], v[0:1], off sc1
	global_load_dwordx4 v[68:71], v[0:1], off offset:16 sc1
	global_load_dwordx4 v[72:75], v[0:1], off offset:32 sc1
	global_load_dwordx4 v[76:79], v[0:1], off offset:48 sc1
	s_sleep 16
	global_load_dwordx4 v[80:83], v[0:1], off sc1
	global_load_dwordx4 v[84:87], v[0:1], off offset:16 sc1
	global_load_dwordx4 v[88:91], v[0:1], off offset:32 sc1
	global_load_dwordx4 v[92:95], v[0:1], off offset:48 sc1
	s_branch .LBB0_2347

.Lpp_join_6:
	s_or_b64 s[8:9], s[8:9], exec
	v_sub_u32_e32 v9, v9, v3
	v_sub_u32_e32 v5, v6, v3
	v_lshrrev_b32_e32 v9, 28, v9
	v_sub_u32_e32 v13, v13, v3
	v_sub_u32_e32 v17, v17, v3
	v_sub_u32_e32 v6, v10, v3
	v_sub_u32_e32 v10, v14, v3
	v_lshrrev_b32_e32 v5, 31, v5
	v_sub_u32_e32 v14, v18, v3
	v_sub_u32_e32 v18, v19, v3
	v_sub_u32_e32 v8, v8, v3
	v_sub_u32_e32 v12, v12, v3
	v_sub_u32_e32 v19, v20, v3
	v_and_b32_e32 v9, 8, v9
	v_and_b32_sdwa v13, v13, s19 dst_sel:DWORD dst_unused:UNUSED_PAD src0_sel:BYTE_3 src1_sel:DWORD
	v_lshrrev_b32_e32 v17, 20, v17
	v_sub_u32_e32 v20, v21, v3
	v_lshrrev_b32_e32 v8, 29, v8
	v_lshrrev_b32_e32 v12, 25, v12
	v_sub_u32_e32 v16, v16, v3
	v_and_b32_e32 v17, 0x800, v17
	v_and_b32_sdwa v20, v20, s20 dst_sel:DWORD dst_unused:UNUSED_PAD src0_sel:WORD_1 src1_sel:DWORD
	v_or3_b32 v5, v13, v5, v9
	v_sub_u32_e32 v7, v7, v3
	v_sub_u32_e32 v11, v11, v3
	v_and_b32_e32 v8, 4, v8
	v_and_b32_e32 v12, 64, v12
	v_lshrrev_b32_e32 v16, 21, v16
	v_lshrrev_b32_e32 v19, 17, v19
	v_or3_b32 v5, v5, v17, v20
	v_lshrrev_b32_e32 v7, 30, v7
	v_lshrrev_b32_e32 v11, 26, v11
	v_sub_u32_e32 v15, v15, v3
	v_and_b32_e32 v16, 0x400, v16
	v_and_b32_e32 v19, 0x4000, v19
	v_or3_b32 v5, v5, v12, v8
	v_and_b32_e32 v7, 2, v7
	v_and_b32_e32 v11, 32, v11
	v_lshrrev_b32_e32 v15, 22, v15
	v_lshrrev_b32_e32 v18, 18, v18
	v_or3_b32 v5, v5, v16, v19
	v_lshrrev_b32_e32 v6, 27, v6
	v_lshrrev_b32_e32 v10, 23, v10
	v_and_b32_e32 v15, 0x200, v15
	v_and_b32_e32 v18, 0x2000, v18
	v_or3_b32 v5, v5, v11, v7
	v_and_b32_e32 v6, 16, v6
	v_and_b32_e32 v10, 0x100, v10
	v_lshrrev_b32_e32 v14, 19, v14
	v_or3_b32 v5, v5, v15, v18
	v_and_b32_e32 v14, 0x1000, v14
	v_or3_b32 v5, v5, v6, v10
	s_waitcnt lgkmcnt(0)
	v_bitop3_b32 v5, v5, v2, v14 bitop3:0xc8
	s_nop 0
	v_readfirstlane_b32 s99, v5
	s_lshr_b32 s99, s99, s98
	s_and_b32 s99, s99, 1
	s_or_b32 s99, s99, s100
	s_cmp_lg_u32 s99, 0
	s_cbranch_scc1 .Lxinv_skip_6
	buffer_inv sc1
	s_waitcnt vmcnt(0)
	s_mov_b32 s100, 1

	.amdhsa_kernel _Z10fwd_kernel4Args
		.amdhsa_group_segment_fixed_size 0
		.amdhsa_private_segment_fixed_size 0
		.amdhsa_kernarg_size 592
		.amdhsa_user_sgpr_count 2
		.amdhsa_user_sgpr_dispatch_ptr 0
		.amdhsa_user_sgpr_queue_ptr 0
		.amdhsa_user_sgpr_kernarg_segment_ptr 1
		.amdhsa_user_sgpr_dispatch_id 0
		.amdhsa_user_sgpr_kernarg_preload_length 0
		.amdhsa_user_sgpr_kernarg_preload_offset 0
		.amdhsa_user_sgpr_private_segment_size 0
		.amdhsa_uses_dynamic_stack 0
		.amdhsa_enable_private_segment 0
		.amdhsa_system_sgpr_workgroup_id_x 1
		.amdhsa_system_sgpr_workgroup_id_y 0
		.amdhsa_system_sgpr_workgroup_id_z 0
		.amdhsa_system_sgpr_workgroup_info 0
		.amdhsa_system_vgpr_workitem_id 0
		.amdhsa_next_free_vgpr 256
		.amdhsa_next_free_sgpr 102
		.amdhsa_accum_offset 256
		.amdhsa_reserve_vcc 1
		.amdhsa_float_round_mode_32 0
		.amdhsa_float_round_mode_16_64 0
		.amdhsa_float_denorm_mode_32 3
		.amdhsa_float_denorm_mode_16_64 3
		.amdhsa_dx10_clamp 1
		.amdhsa_ieee_mode 1
		.amdhsa_fp16_overflow 0
		.amdhsa_tg_split 0
		.amdhsa_exception_fp_ieee_invalid_op 0
		.amdhsa_exception_fp_denorm_src 0
		.amdhsa_exception_fp_ieee_div_zero 0
		.amdhsa_exception_fp_ieee_overflow 0
		.amdhsa_exception_fp_ieee_underflow 0
		.amdhsa_exception_fp_ieee_inexact 0
		.amdhsa_exception_int_div_zero 0
	.end_amdhsa_kernel

amdhsa.kernels:
  - .agpr_count:     0
    .args:
      - .offset:         0
        .size:           336
        .value_kind:     by_value
      - .offset:         336
        .size:           4
        .value_kind:     hidden_block_count_x
      - .offset:         340
        .size:           4
        .value_kind:     hidden_block_count_y
      - .offset:         344
        .size:           4
        .value_kind:     hidden_block_count_z
      - .offset:         348
        .size:           2
        .value_kind:     hidden_group_size_x
      - .offset:         350
        .size:           2
        .value_kind:     hidden_group_size_y
      - .offset:         352
        .size:           2
        .value_kind:     hidden_group_size_z
      - .offset:         354
        .size:           2
        .value_kind:     hidden_remainder_x
      - .offset:         356
        .size:           2
        .value_kind:     hidden_remainder_y
      - .offset:         358
        .size:           2
        .value_kind:     hidden_remainder_z
      - .offset:         376
        .size:           8
        .value_kind:     hidden_global_offset_x
      - .offset:         384
        .size:           8
        .value_kind:     hidden_global_offset_y
      - .offset:         392
        .size:           8
        .value_kind:     hidden_global_offset_z
      - .offset:         400
        .size:           2
        .value_kind:     hidden_grid_dims
      - .offset:         456
        .size:           4
        .value_kind:     hidden_dynamic_lds_size
    .group_segment_fixed_size: 0
    .kernarg_segment_align: 8
    .kernarg_segment_size: 592
    .language:       OpenCL C
    .language_version:
      - 2
      - 0
    .max_flat_workgroup_size: 512
    .name:           _Z10fwd_kernel4Args
    .private_segment_fixed_size: 0
    .sgpr_count:     108
    .sgpr_spill_count: 133
    .symbol:         _Z10fwd_kernel4Args.kd
    .uniform_work_group_size: 1
    .uses_dynamic_stack: false
    .vgpr_count:     256
    .vgpr_spill_count: 0
    .wavefront_size: 64
